# RWKV state recurrence: post-processing moved to the waves that do not share a SIMD with the two state waves (roles of waves 4,5 and 6,7 exchanged)
# baseline (speedup 1.0000x reference)
.LBB0_415:
	s_or_b64 exec, exec, s[4:5]
	s_add_u32 s16, s2, 0x1af00000
	s_addc_u32 s17, s3, 0
	s_ashr_i32 s9, s9, 6
	s_and_b32 s100, s9, 4
	s_lshr_b32 s100, s100, 1
	s_xor_b32 s9, s9, s100
	s_lshl_b32 s15, s10, 11
	s_cmp_lt_i32 s9, 2
	s_cselect_b64 s[12:13], -1, 0
	s_cmp_gt_i32 s9, 1
	s_mov_b64 s[2:3], -1
	s_waitcnt lgkmcnt(0)
	s_barrier
	s_cbranch_scc0 .LBB0_430
	s_cmp_gt_u32 s9, 5
	s_cbranch_scc0 .LBB0_426
	s_add_i32 s5, s9, -6
	s_lshl_b32 s4, s5, 11
	s_add_u32 s2, s11, s4
	s_addc_u32 s3, s18, 0
	s_add_i32 s4, s4, 0
	v_lshlrev_b32_e32 v156, 4, v148
	s_add_i32 s4, s4, 0x22400
	s_mulk_i32 s5, 0x2400
	v_lshl_add_u64 v[0:1], s[2:3], 0, v[156:157]
	s_add_u32 s2, s20, s5
	s_addc_u32 s3, s21, 0
	v_lshl_add_u64 v[2:3], s[2:3], 0, v[156:157]
	s_add_i32 s5, s5, 0
	s_add_i32 s0, s1, s0
	s_mov_b32 s1, 0
	s_branch .LBB0_419
